# NORM phase: the 8 per-batch wave reductions of the shift@W bias GEMV run as interleaved butterflies (same summation order)
# speedup vs baseline: 1.0813x; 1.0055x over previous
.LBB0_178:
	v_lshl_add_u64 v[140:141], s[18:19], 0, v[138:139]
	global_load_dwordx4 v[170:173], v[140:141], off offset:16
	global_load_dwordx4 v[174:177], v[140:141], off
	s_waitcnt vmcnt(1)
	v_lshlrev_b32_e32 v0, 16, v170
	s_waitcnt vmcnt(0)
	v_and_b32_e32 v169, 0xffff0000, v174
	v_lshlrev_b32_e32 v163, 16, v174
	v_and_b32_e32 v161, 0xffff0000, v170
	v_and_b32_e32 v170, 0xffff0000, v176
	s_waitcnt lgkmcnt(14)
	v_mul_f32_e32 v140, v3, v169
	v_lshlrev_b32_e32 v167, 16, v175
	v_lshlrev_b32_e32 v164, 16, v176
	v_fmac_f32_e32 v140, v2, v163
	v_mul_f32_e32 v141, v7, v170
	v_and_b32_e32 v165, 0xffff0000, v175
	v_lshlrev_b32_e32 v168, 16, v177
	v_fmac_f32_e32 v140, v4, v167
	v_fmac_f32_e32 v141, v6, v164
	v_and_b32_e32 v166, 0xffff0000, v177
	v_fmac_f32_e32 v140, v5, v165
	v_fmac_f32_e32 v141, v8, v168
	v_add_f32_e32 v140, 0, v140
	v_fmac_f32_e32 v141, v9, v166
	v_add_f32_e32 v140, v141, v140
	v_mul_f32_e32 v141, v11, v161
	v_lshlrev_b32_e32 v159, 16, v171
	v_fmac_f32_e32 v141, v10, v0
	v_and_b32_e32 v157, 0xffff0000, v171
	v_fmac_f32_e32 v141, v12, v159
	v_and_b32_e32 v162, 0xffff0000, v172
	v_fmac_f32_e32 v141, v13, v157
	s_waitcnt lgkmcnt(0)
	v_lshlrev_b32_e32 v156, 16, v172
	v_add_f32_e32 v140, v141, v140
	v_mul_f32_e32 v141, v15, v162
	v_lshlrev_b32_e32 v160, 16, v173
	v_fmac_f32_e32 v141, v14, v156
	v_and_b32_e32 v158, 0xffff0000, v173
	v_fmac_f32_e32 v141, v16, v160
	v_fmac_f32_e32 v141, v17, v158
	v_add_f32_e32 v180, v141, v140
	v_mul_f32_e32 v171, v19, v169
	v_fmac_f32_e32 v171, v18, v163
	s_waitcnt lgkmcnt(0)
	v_mul_f32_e32 v172, v23, v170
	v_fmac_f32_e32 v171, v20, v167
	v_fmac_f32_e32 v172, v22, v164
	v_fmac_f32_e32 v171, v21, v165
	v_fmac_f32_e32 v172, v24, v168
	v_add_f32_e32 v171, 0, v171
	v_fmac_f32_e32 v172, v25, v166
	v_add_f32_e32 v171, v172, v171
	v_mul_f32_e32 v172, v27, v161
	v_fmac_f32_e32 v172, v26, v0
	v_fmac_f32_e32 v172, v28, v159
	v_fmac_f32_e32 v172, v29, v157
	v_add_f32_e32 v171, v172, v171
	v_mul_f32_e32 v172, v31, v162
	v_fmac_f32_e32 v172, v30, v156
	v_fmac_f32_e32 v172, v32, v160
	v_fmac_f32_e32 v172, v33, v158
	v_add_f32_e32 v181, v172, v171
	v_mul_f32_e32 v171, v35, v169
	v_fmac_f32_e32 v171, v34, v163
	s_waitcnt lgkmcnt(0)
	v_mul_f32_e32 v172, v39, v170
	v_fmac_f32_e32 v171, v36, v167
	v_fmac_f32_e32 v172, v38, v164
	v_fmac_f32_e32 v171, v37, v165
	v_fmac_f32_e32 v172, v40, v168
	v_add_f32_e32 v171, 0, v171
	v_fmac_f32_e32 v172, v41, v166
	v_add_f32_e32 v171, v172, v171
	v_mul_f32_e32 v172, v43, v161
	v_fmac_f32_e32 v172, v42, v0
	v_fmac_f32_e32 v172, v44, v159
	v_fmac_f32_e32 v172, v45, v157
	v_add_f32_e32 v171, v172, v171
	v_mul_f32_e32 v172, v47, v162
	v_fmac_f32_e32 v172, v46, v156
	v_fmac_f32_e32 v172, v48, v160
	v_fmac_f32_e32 v172, v49, v158
	v_add_f32_e32 v182, v172, v171
	v_mul_f32_e32 v171, v51, v169
	v_fmac_f32_e32 v171, v50, v163
	s_waitcnt lgkmcnt(0)
	v_mul_f32_e32 v172, v55, v170
	v_fmac_f32_e32 v171, v52, v167
	v_fmac_f32_e32 v172, v54, v164
	v_fmac_f32_e32 v171, v53, v165
	v_fmac_f32_e32 v172, v56, v168
	v_add_f32_e32 v171, 0, v171
	v_fmac_f32_e32 v172, v57, v166
	v_add_f32_e32 v171, v172, v171
	v_mul_f32_e32 v172, v59, v161
	v_fmac_f32_e32 v172, v58, v0
	v_fmac_f32_e32 v172, v60, v159
	v_fmac_f32_e32 v172, v61, v157
	v_add_f32_e32 v171, v172, v171
	v_mul_f32_e32 v172, v63, v162
	v_fmac_f32_e32 v172, v62, v156
	v_fmac_f32_e32 v172, v64, v160
	v_fmac_f32_e32 v172, v65, v158
	v_add_f32_e32 v183, v172, v171
	v_mul_f32_e32 v171, v67, v169
	v_fmac_f32_e32 v171, v66, v163
	s_waitcnt lgkmcnt(0)
	v_mul_f32_e32 v172, v71, v170
	v_fmac_f32_e32 v171, v68, v167
	v_fmac_f32_e32 v172, v70, v164
	v_fmac_f32_e32 v171, v69, v165
	v_fmac_f32_e32 v172, v72, v168
	v_add_f32_e32 v171, 0, v171
	v_fmac_f32_e32 v172, v73, v166
	v_add_f32_e32 v171, v172, v171
	v_mul_f32_e32 v172, v75, v161
	v_fmac_f32_e32 v172, v74, v0
	v_fmac_f32_e32 v172, v76, v159
	v_fmac_f32_e32 v172, v77, v157
	v_add_f32_e32 v171, v172, v171
	v_mul_f32_e32 v172, v79, v162
	v_fmac_f32_e32 v172, v78, v156
	v_fmac_f32_e32 v172, v80, v160
	v_fmac_f32_e32 v172, v81, v158
	v_add_f32_e32 v184, v172, v171
	v_mul_f32_e32 v171, v83, v169
	v_fmac_f32_e32 v171, v82, v163
	s_waitcnt lgkmcnt(0)
	v_mul_f32_e32 v172, v87, v170
	v_fmac_f32_e32 v171, v84, v167
	v_fmac_f32_e32 v172, v86, v164
	v_fmac_f32_e32 v171, v85, v165
	v_fmac_f32_e32 v172, v88, v168
	v_add_f32_e32 v171, 0, v171
	v_fmac_f32_e32 v172, v89, v166
	v_add_f32_e32 v171, v172, v171
	v_mul_f32_e32 v172, v91, v161
	v_fmac_f32_e32 v172, v90, v0
	v_fmac_f32_e32 v172, v92, v159
	v_fmac_f32_e32 v172, v93, v157
	v_add_f32_e32 v171, v172, v171
	v_mul_f32_e32 v172, v95, v162
	v_fmac_f32_e32 v172, v94, v156
	v_fmac_f32_e32 v172, v96, v160
	v_fmac_f32_e32 v172, v97, v158
	v_add_f32_e32 v185, v172, v171
	v_mul_f32_e32 v171, v99, v169
	v_fmac_f32_e32 v171, v98, v163
	s_waitcnt lgkmcnt(0)
	v_mul_f32_e32 v172, v103, v170
	v_fmac_f32_e32 v171, v100, v167
	v_fmac_f32_e32 v172, v102, v164
	v_fmac_f32_e32 v171, v101, v165
	v_fmac_f32_e32 v172, v104, v168
	v_add_f32_e32 v171, 0, v171
	v_fmac_f32_e32 v172, v105, v166
	v_add_f32_e32 v171, v172, v171
	v_mul_f32_e32 v172, v107, v161
	v_fmac_f32_e32 v172, v106, v0
	v_fmac_f32_e32 v172, v108, v159
	v_fmac_f32_e32 v172, v109, v157
	v_add_f32_e32 v171, v172, v171
	v_mul_f32_e32 v172, v111, v162
	v_fmac_f32_e32 v172, v110, v156
	v_fmac_f32_e32 v172, v112, v160
	v_fmac_f32_e32 v172, v113, v158
	v_add_f32_e32 v186, v172, v171
	v_mul_f32_e32 v169, v115, v169
	v_fmac_f32_e32 v169, v114, v163
	v_fmac_f32_e32 v169, v116, v167
	v_mul_f32_e32 v161, v123, v161
	v_fmac_f32_e32 v169, v117, v165
	v_mul_f32_e32 v165, v119, v170
	v_fmac_f32_e32 v161, v122, v0
	v_fmac_f32_e32 v165, v118, v164
	v_fmac_f32_e32 v161, v124, v159
	v_fmac_f32_e32 v165, v120, v168
	v_fmac_f32_e32 v161, v125, v157
	v_mul_f32_e32 v157, v127, v162
	v_add_f32_e32 v163, 0, v169
	v_fmac_f32_e32 v165, v121, v166
	v_fmac_f32_e32 v157, v126, v156
	v_add_f32_e32 v163, v165, v163
	v_fmac_f32_e32 v157, v128, v160
	v_add_f32_e32 v0, v161, v163
	v_fmac_f32_e32 v157, v129, v158
	v_add_f32_e32 v187, v157, v0
	ds_bpermute_b32 v188, v146, v180
	ds_bpermute_b32 v189, v146, v181
	ds_bpermute_b32 v190, v146, v182
	ds_bpermute_b32 v191, v146, v183
	ds_bpermute_b32 v192, v146, v184
	ds_bpermute_b32 v193, v146, v185
	ds_bpermute_b32 v194, v146, v186
	ds_bpermute_b32 v195, v146, v187
	s_waitcnt lgkmcnt(0)
	v_add_f32_e32 v180, v180, v188
	v_add_f32_e32 v181, v181, v189
	v_add_f32_e32 v182, v182, v190
	v_add_f32_e32 v183, v183, v191
	v_add_f32_e32 v184, v184, v192
	v_add_f32_e32 v185, v185, v193
	v_add_f32_e32 v186, v186, v194
	v_add_f32_e32 v187, v187, v195
	ds_bpermute_b32 v188, v147, v180
	ds_bpermute_b32 v189, v147, v181
	ds_bpermute_b32 v190, v147, v182
	ds_bpermute_b32 v191, v147, v183
	ds_bpermute_b32 v192, v147, v184
	ds_bpermute_b32 v193, v147, v185
	ds_bpermute_b32 v194, v147, v186
	ds_bpermute_b32 v195, v147, v187
	s_waitcnt lgkmcnt(0)
	v_add_f32_e32 v180, v180, v188
	v_add_f32_e32 v181, v181, v189
	v_add_f32_e32 v182, v182, v190
	v_add_f32_e32 v183, v183, v191
	v_add_f32_e32 v184, v184, v192
	v_add_f32_e32 v185, v185, v193
	v_add_f32_e32 v186, v186, v194
	v_add_f32_e32 v187, v187, v195
	ds_bpermute_b32 v188, v148, v180
	ds_bpermute_b32 v189, v148, v181
	ds_bpermute_b32 v190, v148, v182
	ds_bpermute_b32 v191, v148, v183
	ds_bpermute_b32 v192, v148, v184
	ds_bpermute_b32 v193, v148, v185
	ds_bpermute_b32 v194, v148, v186
	ds_bpermute_b32 v195, v148, v187
	s_waitcnt lgkmcnt(0)
	v_add_f32_e32 v180, v180, v188
	v_add_f32_e32 v181, v181, v189
	v_add_f32_e32 v182, v182, v190
	v_add_f32_e32 v183, v183, v191
	v_add_f32_e32 v184, v184, v192
	v_add_f32_e32 v185, v185, v193
	v_add_f32_e32 v186, v186, v194
	v_add_f32_e32 v187, v187, v195
	ds_bpermute_b32 v188, v149, v180
	ds_bpermute_b32 v189, v149, v181
	ds_bpermute_b32 v190, v149, v182
	ds_bpermute_b32 v191, v149, v183
	ds_bpermute_b32 v192, v149, v184
	ds_bpermute_b32 v193, v149, v185
	ds_bpermute_b32 v194, v149, v186
	ds_bpermute_b32 v195, v149, v187
	s_waitcnt lgkmcnt(0)
	v_add_f32_e32 v180, v180, v188
	v_add_f32_e32 v181, v181, v189
	v_add_f32_e32 v182, v182, v190
	v_add_f32_e32 v183, v183, v191
	v_add_f32_e32 v184, v184, v192
	v_add_f32_e32 v185, v185, v193
	v_add_f32_e32 v186, v186, v194
	v_add_f32_e32 v187, v187, v195
	ds_bpermute_b32 v188, v150, v180
	ds_bpermute_b32 v189, v150, v181
	ds_bpermute_b32 v190, v150, v182
	ds_bpermute_b32 v191, v150, v183
	ds_bpermute_b32 v192, v150, v184
	ds_bpermute_b32 v193, v150, v185
	ds_bpermute_b32 v194, v150, v186
	ds_bpermute_b32 v195, v150, v187
	s_waitcnt lgkmcnt(0)
	v_add_f32_e32 v180, v180, v188
	v_add_f32_e32 v181, v181, v189
	v_add_f32_e32 v182, v182, v190
	v_add_f32_e32 v183, v183, v191
	v_add_f32_e32 v184, v184, v192
	v_add_f32_e32 v185, v185, v193
	v_add_f32_e32 v186, v186, v194
	v_add_f32_e32 v187, v187, v195
	ds_bpermute_b32 v188, v151, v180
	ds_bpermute_b32 v189, v151, v181
	ds_bpermute_b32 v190, v151, v182
	ds_bpermute_b32 v191, v151, v183
	ds_bpermute_b32 v192, v151, v184
	ds_bpermute_b32 v193, v151, v185
	ds_bpermute_b32 v194, v151, v186
	ds_bpermute_b32 v195, v151, v187
	s_waitcnt lgkmcnt(0)
	v_add_f32_e32 v180, v180, v188
	v_add_f32_e32 v181, v181, v189
	v_add_f32_e32 v182, v182, v190
	v_add_f32_e32 v183, v183, v191
	v_add_f32_e32 v184, v184, v192
	v_add_f32_e32 v185, v185, v193
	v_add_f32_e32 v186, v186, v194
	v_add_f32_e32 v187, v187, v195
	v_lshl_add_u64 v[140:141], s[18:19], 0, v[136:137]
	s_and_saveexec_b64 s[2:3], s[38:39]
	s_cbranch_execz .LBB0_177
	v_add_co_u32_e32 v196, vcc, 0xf700000, v140
	s_nop 1
	v_addc_co_u32_e32 v197, vcc, 0, v141, vcc
	global_store_dword v[196:197], v180, off
	v_add_co_u32_e32 v196, vcc, 0xf704000, v140
	s_nop 1
	v_addc_co_u32_e32 v197, vcc, 0, v141, vcc
	global_store_dword v[196:197], v181, off
	v_add_co_u32_e32 v196, vcc, 0xf708000, v140
	s_nop 1
	v_addc_co_u32_e32 v197, vcc, 0, v141, vcc
	global_store_dword v[196:197], v182, off
	v_add_co_u32_e32 v196, vcc, 0xf70c000, v140
	s_nop 1
	v_addc_co_u32_e32 v197, vcc, 0, v141, vcc
	global_store_dword v[196:197], v183, off
	v_add_co_u32_e32 v196, vcc, 0xf710000, v140
	s_nop 1
	v_addc_co_u32_e32 v197, vcc, 0, v141, vcc
	global_store_dword v[196:197], v184, off
	v_add_co_u32_e32 v196, vcc, 0xf714000, v140
	s_nop 1
	v_addc_co_u32_e32 v197, vcc, 0, v141, vcc
	global_store_dword v[196:197], v185, off
	v_add_co_u32_e32 v196, vcc, 0xf718000, v140
	s_nop 1
	v_addc_co_u32_e32 v197, vcc, 0, v141, vcc
	global_store_dword v[196:197], v186, off
	v_add_co_u32_e32 v196, vcc, 0xf71c000, v140
	s_nop 1
	v_addc_co_u32_e32 v197, vcc, 0, v141, vcc
	global_store_dword v[196:197], v187, off
	s_branch .LBB0_177
